# v43 + dead per-XCD relay address arithmetic removed from the grid-barrier leader exit (instruction-count trim)
# baseline (speedup 1.0000x reference)
.LBB0_114:
	s_or_b64 exec, exec, s[0:1]
	s_waitcnt vmcnt(1) lgkmcnt(0)

.LBB0_117:
	s_or_b64 exec, exec, s[4:5]
	s_waitcnt vmcnt(1) lgkmcnt(0)
